# seq sample-state loads batched (8 loads, one wait) in ssd_seq/gla_seq; ssd_pre D-skip loads hoisted, per-head vmcnt(0) store drains removed
# baseline (speedup 1.0000x reference)
; __device__ __forceinline__ bfr f2bf(float f) { return (bfr)(pack2(f, f) & 0xffffu); }
; __device__ void gla_seq(const KP& p, int l, int s, int h, int vq) {
;     ...
;   f32x4 Sacc[2];
; #pragma unroll
;   for (int vt = 0; vt < 2; ++vt)
; #pragma unroll
;     for (int j = 0; j < 4; ++j) {
;       int k = 16 * w + fq * 4 + j, v = vt * 16 + fr;
;       float x = 0.f;
;       if (!prompt) x = p.in[4][((((size_t)l * 8 + sb) * 4 + h) * 128 + k) * 128 + vq * 32 + v];
;       Sacc[vt][j] = x;
;       STs[v * 136 + k] = f2bf(x);
;     }
;   __syncthreads();
.LBB0_332:
	s_lshl_b32 s38, s52, 2
	s_and_b32 s38, s38, 28
	s_bfe_u32 s56, s84, 0x20002
	s_or_b32 s38, s40, s38
	s_lshl_b32 s3, s84, 5
	s_or_b32 s38, s38, s56
	s_mov_b32 s39, s41
	v_readlane_b32 s16, v254, 56
	s_and_b32 s3, s3, 0x60
	s_lshl_b64 s[52:53], s[38:39], 16
	v_readlane_b32 s24, v255, 0
	v_readlane_b32 s25, v255, 1
	s_add_u32 s38, s24, s52
	v_ashrrev_i32_e32 v181, 6, v0
	s_waitcnt vmcnt(0)
	v_bfe_u32 v4, v0, 4, 2
	s_addc_u32 s39, s25, s53
	s_lshl_b32 s85, s3, 2
	v_and_b32_e32 v175, 15, v0
	v_lshlrev_b32_e32 v151, 4, v181
	v_lshlrev_b32_e32 v153, 2, v4
	s_add_u32 s38, s38, s85
	v_or_b32_e32 v138, v153, v151
	s_addc_u32 s39, s39, 0
	v_lshlrev_b32_e32 v140, 2, v175
	v_mov_b32_e32 v141, v1
	v_cndmask_b32_e64 v5, 0, 1, s[76:77]
	v_lshl_add_u64 v[2:3], s[38:39], 0, v[140:141]
	v_mov_b32_e32 v11, 0
	v_cmp_ne_u32_e64 s[38:39], 1, v5
	s_andn2_b64 vcc, exec, s[76:77]
	v_ashrrev_i32_e32 v139, 31, v138
	v_mov_b32_e32 v10, 0
	v_readlane_b32 s17, v254, 57
	v_readlane_b32 s18, v254, 58
	v_readlane_b32 s19, v254, 59
	v_readlane_b32 s20, v254, 60
	v_readlane_b32 s21, v254, 61
	v_readlane_b32 s22, v254, 62
	v_readlane_b32 s23, v254, 63
	v_readlane_b32 s26, v255, 2
	v_readlane_b32 s27, v255, 3
	v_readlane_b32 s28, v255, 4
	v_readlane_b32 s29, v255, 5
	v_readlane_b32 s30, v255, 6
	v_readlane_b32 s31, v255, 7
	v_mov_b32_e32 v12, 0
	v_mov_b32_e32 v13, 0
	v_mov_b32_e32 v22, 0
	v_mov_b32_e32 v23, 0
	v_mov_b32_e32 v24, 0
	v_mov_b32_e32 v25, 0
	s_cbranch_vccnz .LBB0_334
	v_lshlrev_b64 v[6:7], 9, v[138:139]
	v_lshl_add_u64 v[6:7], v[2:3], 0, v[6:7]
	global_load_dword v10, v[6:7], off
	global_load_dword v11, v[6:7], off offset:512
	global_load_dword v12, v[6:7], off offset:1024
	global_load_dword v13, v[6:7], off offset:1536
	global_load_dword v22, v[6:7], off offset:64
	global_load_dword v23, v[6:7], off offset:576
	global_load_dword v24, v[6:7], off offset:1088
	global_load_dword v25, v[6:7], off offset:1600
	s_waitcnt vmcnt(0)
.LBB0_334:
	s_movk_i32 s57, 0x110
	v_mad_u32_u24 v5, v175, s57, 0
	v_or_b32_e32 v142, 1, v138
	s_waitcnt vmcnt(0)
	v_cvt_pk_bf16_f32 v6, v10, s0
	v_lshl_add_u32 v5, v138, 1, v5
	s_and_b64 vcc, exec, s[38:39]
	v_ashrrev_i32_e32 v143, 31, v142
	ds_write_b16 v5, v6
	s_branch .LBB0_336
.LBB0_336:
	v_or_b32_e32 v144, 2, v138
	s_waitcnt vmcnt(0)
	v_cvt_pk_bf16_f32 v6, v11, s0
	s_waitcnt lgkmcnt(0)
	s_and_b64 vcc, exec, s[38:39]
	v_ashrrev_i32_e32 v145, 31, v144
	ds_write_b16 v5, v6 offset:2
	s_branch .LBB0_338
.LBB0_338:
	v_or_b32_e32 v146, 3, v138
	s_waitcnt vmcnt(0)
	v_cvt_pk_bf16_f32 v6, v12, s0
	s_and_b64 vcc, exec, s[38:39]
	v_ashrrev_i32_e32 v147, 31, v146
	ds_write_b16 v5, v6 offset:4
	s_branch .LBB0_340
.LBB0_340:
	s_waitcnt vmcnt(0)
	v_cvt_pk_bf16_f32 v6, v13, s0
	s_and_b64 vcc, exec, s[38:39]
	ds_write_b16 v5, v6 offset:6
	s_branch .LBB0_342
.LBB0_342:
	s_waitcnt vmcnt(0)
	v_cvt_pk_bf16_f32 v6, v22, s0
	s_and_b64 vcc, exec, s[38:39]
	ds_write_b16 v5, v6 offset:4352
	s_branch .LBB0_344
.LBB0_344:
	v_add_u32_e32 v5, 0x1100, v5
	s_waitcnt vmcnt(0)
	v_cvt_pk_bf16_f32 v6, v23, s0
	s_and_b64 vcc, exec, s[38:39]
	ds_write_b16 v5, v6 offset:2
	s_branch .LBB0_346
.LBB0_346:
	s_waitcnt vmcnt(0)
	v_cvt_pk_bf16_f32 v6, v24, s0
	s_and_b64 vcc, exec, s[38:39]
	ds_write_b16 v5, v6 offset:4
	s_branch .LBB0_348

; __device__ __forceinline__ bfr f2bf(float f) { return (bfr)(pack2(f, f) & 0xffffu); }
; __device__ void ssd_seq(const KP& p, int l, int s, int h, int ph) {
;     ...
;   f32x4 Sacc[2];
; #pragma unroll
;   for (int pt = 0; pt < 2; ++pt)
; #pragma unroll
;     for (int j = 0; j < 4; ++j) {
;       int pp = pt * 16 + fq * 4 + j, n = 16 * w + fr;
;       float v = 0.f;
;       if (!prompt) v = p.in[3][((((size_t)l * 8 + sb) * 8 + h) * 64 + ph * 32 + pp) * 128 + n];
;       Sacc[pt][j] = v;
;       Sbs[pp * 136 + n] = f2bf(v);
;     }
;   __syncthreads();
.LBB0_386:
	s_waitcnt vmcnt(0)
	v_ashrrev_i32_e32 v50, 2, v0
	s_lshl_b32 s0, s14, 3
	s_bfe_u32 s3, s84, 0x30001
	v_bfi_b32 v2, -16, v50, v0
	s_or_b32 s0, s46, s0
	v_readlane_b32 s16, v254, 56
	s_lshl_b32 s2, s84, 5
	s_or_b32 s52, s0, s3
	s_mov_b32 s53, s47
	v_ashrrev_i32_e32 v3, 31, v2
	v_readlane_b32 s22, v254, 62
	v_readlane_b32 s23, v254, 63
	v_bfe_u32 v104, v0, 4, 2
	s_and_b32 s85, s2, 32
	s_lshl_b64 s[74:75], s[52:53], 6
	v_lshl_add_u64 v[4:5], v[2:3], 2, s[22:23]
	v_cndmask_b32_e64 v3, 0, 1, s[76:77]
	v_lshlrev_b32_e32 v91, 2, v104
	s_or_b32 s14, s74, s85
	v_mov_b32_e32 v43, 0
	v_cmp_ne_u32_e64 s[0:1], 1, v3
	s_andn2_b64 vcc, exec, s[76:77]
	v_mov_b32_e32 v42, 0
	v_readlane_b32 s17, v254, 57
	v_readlane_b32 s18, v254, 58
	v_readlane_b32 s19, v254, 59
	v_readlane_b32 s20, v254, 60
	v_readlane_b32 s21, v254, 61
	v_readlane_b32 s24, v255, 0
	v_readlane_b32 s25, v255, 1
	v_readlane_b32 s26, v255, 2
	v_readlane_b32 s27, v255, 3
	v_readlane_b32 s28, v255, 4
	v_readlane_b32 s29, v255, 5
	v_readlane_b32 s30, v255, 6
	v_readlane_b32 s31, v255, 7
	v_mov_b32_e32 v44, 0
	v_mov_b32_e32 v45, 0
	v_mov_b32_e32 v46, 0
	v_mov_b32_e32 v47, 0
	v_mov_b32_e32 v48, 0
	v_mov_b32_e32 v49, 0
	s_cbranch_vccnz .LBB0_388
	v_or_b32_e32 v6, s14, v91
	v_mov_b32_e32 v7, s75
	v_lshlrev_b64 v[6:7], 9, v[6:7]
	v_lshl_add_u64 v[6:7], v[4:5], 0, v[6:7]
	global_load_dword v42, v[6:7], off
	global_load_dword v43, v[6:7], off offset:512
	global_load_dword v44, v[6:7], off offset:1024
	global_load_dword v45, v[6:7], off offset:1536
	v_add_co_u32_e32 v8, vcc, 0x2000, v6
	s_nop 1
	v_addc_co_u32_e32 v9, vcc, 0, v7, vcc
	global_load_dword v46, v[8:9], off
	global_load_dword v47, v[8:9], off offset:512
	global_load_dword v48, v[8:9], off offset:1024
	global_load_dword v49, v[8:9], off offset:1536
	s_waitcnt vmcnt(0)
.LBB0_388:
	v_lshl_add_u32 v3, v2, 1, 0
	s_movk_i32 s15, 0x440
	s_waitcnt vmcnt(0)
	v_cvt_pk_bf16_f32 v6, v42, s0
	v_mad_u32_u24 v7, v104, s15, v3
	ds_write_b16 v7, v6
	s_and_b64 vcc, exec, s[0:1]
	v_or_b32_e32 v6, 1, v91
	s_branch .LBB0_390
.LBB0_390:
	s_movk_i32 s15, 0x110
	s_waitcnt vmcnt(0)
	v_cvt_pk_bf16_f32 v7, v43, s0
	s_waitcnt lgkmcnt(0)
	v_mad_u32_u24 v8, v6, s15, v3
	s_and_b64 vcc, exec, s[0:1]
	ds_write_b16 v8, v7
	s_branch .LBB0_392
.LBB0_392:
	v_mul_u32_u24_e32 v106, 0x110, v6
	s_waitcnt vmcnt(0)
	v_cvt_pk_bf16_f32 v6, v44, s0
	v_add_u32_e32 v3, v106, v3
	s_and_b64 vcc, exec, s[0:1]
	ds_write_b16 v3, v6 offset:272
	s_branch .LBB0_394
.LBB0_394:
	s_waitcnt vmcnt(0)
	v_cvt_pk_bf16_f32 v6, v45, s0
	s_and_b64 vcc, exec, s[0:1]
	ds_write_b16 v3, v6 offset:544
	s_branch .LBB0_396
.LBB0_396:
	s_waitcnt vmcnt(0)
	v_cvt_pk_bf16_f32 v6, v46, s0
	s_and_b64 vcc, exec, s[0:1]
	ds_write_b16 v3, v6 offset:4080
	s_branch .LBB0_398
.LBB0_398:
	s_waitcnt vmcnt(0)
	v_cvt_pk_bf16_f32 v6, v47, s0
	s_and_b64 vcc, exec, s[0:1]
	ds_write_b16 v3, v6 offset:4352
	s_branch .LBB0_400
.LBB0_400:
	s_waitcnt vmcnt(0)
	v_cvt_pk_bf16_f32 v6, v48, s0
	s_and_b64 vcc, exec, s[0:1]
	ds_write_b16 v3, v6 offset:4624
	s_branch .LBB0_402

; __device__ __forceinline__ bfr f2bf(float f) { return (bfr)(pack2(f, f) & 0xffffu); }
; __device__ __forceinline__ float bf2f(bfr b) { return __uint_as_float(((unsigned)b) << 16); }
; __device__ void ssd_pre(const KP& p, int l, int cid, int g) {
;     ...
; #pragma unroll
;     for (int q = 0; q < 2; ++q) {
;       int t = w * 2 + q, ti = t >> 2, tp = t & 3;
;       f32x4 a = f32x4{0.f, 0.f, 0.f, 0.f};
;       a = mma_lds(Gs + ti * 16 * 72, 72, xTs + (hh * 64 + tp * 16) * 72, 72, 2, a, fr, fq);
;       int pp = tp * 16 + fr;
; #pragma unroll
;       for (int j = 0; j < 4; ++j) {
;         int i = ti * 16 + fq * 4 + j;
;         float y = a[j] + Dh * bf2f(xTs[(hh * 64 + pp) * 72 + i]);
;         mix[(size_t)(r0 + i) * DM + h * 64 + pp] = f2bf(y);
;       }
;     }
;     __syncthreads();
.LBB0_413:
	s_or_b64 exec, exec, s[0:1]
	ds_write_b16 v25, v2 offset:432
	s_waitcnt lgkmcnt(0)
	s_barrier
	ds_read_b128 v[2:5], v28
	ds_read_b128 v[6:9], v33 offset:27648
	ds_read_b128 v[20:23], v28 offset:64
	ds_read_b64 v[34:35], v31 offset:27648
	ds_read_b128 v[24:27], v33 offset:27712
	s_or_b32 s0, s2, 0x180
	s_add_u32 s0, s42, s0
	s_waitcnt lgkmcnt(3)
	v_mfma_f32_16x16x32_bf16 v[6:9], v[2:5], v[6:9], 0
	s_addc_u32 s1, s43, 0
	v_lshl_add_u64 v[36:37], v[0:1], 1, s[0:1]
	s_waitcnt lgkmcnt(1)
	v_lshlrev_b32_e32 v0, 16, v34
	s_waitcnt lgkmcnt(0)
	v_mfma_f32_16x16x32_bf16 v[6:9], v[20:23], v[24:27], v[6:9]
	v_lshl_add_u64 v[24:25], v[36:37], 0, v[12:13]
	ds_read_b64 v[38:39], v29 offset:27648
	s_nop 0
	s_nop 4
	v_fma_f32 v0, v32, v0, v6
	v_cvt_pk_bf16_f32 v0, v0, s0
	global_store_short v[24:25], v0, off
	ds_read_b128 v[24:27], v30 offset:27648
	v_and_b32_e32 v0, 0xffff0000, v34
	v_fma_f32 v0, v32, v0, v7
	ds_read_b128 v[28:31], v30 offset:27712
	v_cvt_pk_bf16_f32 v0, v0, s0
	v_lshl_add_u64 v[6:7], v[36:37], 0, v[14:15]
	s_waitcnt lgkmcnt(1)
	v_mfma_f32_16x16x32_bf16 v[2:5], v[2:5], v[24:27], 0
	global_store_short v[6:7], v0, off
	v_lshlrev_b32_e32 v0, 16, v35
	v_fma_f32 v0, v32, v0, v8
	v_cvt_pk_bf16_f32 v0, v0, s0
	v_lshl_add_u64 v[6:7], v[36:37], 0, v[16:17]
	global_store_short v[6:7], v0, off
	v_and_b32_e32 v0, 0xffff0000, v35
	s_waitcnt lgkmcnt(0)
	v_mfma_f32_16x16x32_bf16 v[2:5], v[20:23], v[28:31], v[2:5]
	v_fmac_f32_e32 v9, v32, v0
	v_cvt_pk_bf16_f32 v0, v9, s0
	v_lshl_add_u64 v[6:7], v[36:37], 0, v[18:19]
	global_store_short v[6:7], v0, off
	v_lshlrev_b32_e32 v0, 16, v38
	v_lshl_add_u64 v[6:7], v[10:11], 1, s[0:1]
	s_nop 1
	v_fma_f32 v0, v32, v0, v2
	v_cvt_pk_bf16_f32 v0, v0, s0
	v_lshl_add_u64 v[8:9], v[6:7], 0, v[12:13]
	global_store_short v[8:9], v0, off
	v_and_b32_e32 v0, 0xffff0000, v38
	v_fma_f32 v0, v32, v0, v3
	v_cvt_pk_bf16_f32 v0, v0, s0
	v_lshl_add_u64 v[2:3], v[6:7], 0, v[14:15]
	global_store_short v[2:3], v0, off
	v_lshlrev_b32_e32 v0, 16, v39
	v_fma_f32 v0, v32, v0, v4
	v_cvt_pk_bf16_f32 v0, v0, s0
	v_lshl_add_u64 v[2:3], v[6:7], 0, v[16:17]
	global_store_short v[2:3], v0, off
	v_and_b32_e32 v0, 0xffff0000, v39
	v_fmac_f32_e32 v5, v32, v0
	v_cvt_pk_bf16_f32 v0, v5, s0
	v_readlane_b32 s0, v255, 43
	s_add_i32 s93, s93, s0
	v_lshl_add_u64 v[2:3], v[6:7], 0, v[18:19]
	s_cmpk_gt_i32 s93, 0x41f
	global_store_short v[2:3], v0, off
	s_barrier
	v_readlane_b32 s1, v255, 44
	s_cbranch_scc1 .LBB0_778

; __device__ __forceinline__ unsigned pack2(float a, float b) { f32v2_t v = {a, b}; bf16v2_t r = __builtin_convertvector(v, bf16v2_t); return __builtin_bit_cast(unsigned, r); }
; __device__ void ssd_pre(const KP& p, int l, int cid, int g) {
;     ...
; #pragma unroll
;   for (int it = 0; it < 2; ++it) {
;     int e = tid + 512 * it;
;     { int i = e >> 4, sg = e & 15; *(u32x4*)(proj + (size_t)(r0 + i) * NIN + 1280 + g * 128 + sg * 8) = *(const u32x4*)(Cs + i * 136 + sg * 8); }
;     { int n = e >> 3, sg = e & 7; *(u32x4*)(proj + (size_t)(r0 + (n >> 1)) * NIN + 1024 + g * 128 + (n & 1) * 64 + sg * 8) = *(const u32x4*)(BTs + n * 72 + sg * 8); }
;   }
; #pragma unroll
;   for (int it = 0; it < 4; ++it) {
;     int e = tid + 512 * it, xr = e >> 3, sg = e & 7, hh = xr >> 6, pp = xr & 63;
;     u32x4 v = *(const u32x4*)(xTs + xr * 72 + sg * 8), o;
; #pragma unroll
;     for (int k = 0; k < 4; ++k) {
;       float e0 = ev[hh * 64 + sg * 8 + 2 * k], e1 = ev[hh * 64 + sg * 8 + 2 * k + 1];
;       o[k] = pack2(__uint_as_float(v[k] << 16) * e0, __uint_as_float(v[k] & 0xffff0000u) * e1);
;     }
;     *(u32x4*)(proj + (size_t)(r0 + pp) * NIN + 512 + (g * 4 + hh) * 64 + sg * 8) = o;
;   }
.LBB0_713:
	s_or_b64 exec, exec, s[40:41]
	v_lshlrev_b32_e32 v0, 4, v27
	v_and_b32_e32 v0, 0xf0, v0
	v_lshlrev_b32_e32 v10, 3, v27
	v_add_u32_e32 v30, 0, v0
	v_ashrrev_i32_e32 v11, 4, v27
	s_movk_i32 s3, 0x110
	v_and_b32_e32 v29, 56, v10
	v_mad_u64_u32 v[12:13], s[0:1], v11, s3, v[30:31]
	v_lshlrev_b32_e32 v10, 1, v29
	ds_read_b128 v[18:21], v12
	v_add_u32_e32 v38, 0, v10
	v_add_u32_e32 v11, s86, v11
	v_mov_b64_e32 v[12:13], s[36:37]
	s_movk_i32 s14, 0x1c00
	s_movk_i32 s2, 0x90
	v_mad_i64_i32 v[22:23], s[0:1], v11, s14, v[12:13]
	s_lshl_b32 s72, s84, 8
	v_mad_u64_u32 v[36:37], s[0:1], v28, s2, v[38:39]
	v_lshl_add_u64 v[32:33], v[22:23], 0, s[72:73]
	ds_read_b128 v[22:25], v36 offset:34816
	v_lshl_add_u64 v[34:35], v[32:33], 0, v[0:1]
	v_lshlrev_b32_e32 v11, 7, v28
	s_waitcnt lgkmcnt(1)
	global_store_dwordx4 v[34:35], v[18:21], off offset:2560
	v_add_u32_e32 v39, 0x200, v27
	v_ashrrev_i32_e32 v42, 3, v39
	v_and_b32_e32 v18, 0x80, v11
	v_mov_b32_e32 v19, v1
	v_lshl_add_u64 v[18:19], v[32:33], 0, v[18:19]
	v_mov_b32_e32 v11, v1
	v_lshl_add_u64 v[18:19], v[18:19], 0, v[10:11]
	s_waitcnt lgkmcnt(0)
	global_store_dwordx4 v[18:19], v[22:25], off offset:2048
	v_mad_u64_u32 v[34:35], s[0:1], v42, s2, v[38:39]
	s_nop 0
	v_ashrrev_i32_e32 v22, 4, v39
	v_mad_u64_u32 v[18:19], s[0:1], v22, s3, v[30:31]
	ds_read_b128 v[18:21], v18
	v_add_u32_e32 v22, s86, v22
	v_mad_i64_i32 v[22:23], s[0:1], v22, s14, v[12:13]
	v_lshl_add_u64 v[30:31], v[22:23], 0, s[72:73]
	v_lshl_add_u64 v[32:33], v[30:31], 0, v[0:1]
	v_lshlrev_b32_e32 v0, 7, v42
	v_and_b32_e32 v0, 0x80, v0
	s_add_i32 s0, 0, 0x18c00
	ds_read_b128 v[22:25], v36 offset:53248
	s_waitcnt lgkmcnt(1)
	global_store_dwordx4 v[32:33], v[18:21], off offset:2560
	ds_read_b128 v[18:21], v34 offset:34816
	v_lshl_add_u64 v[30:31], v[30:31], 0, v[0:1]
	v_lshl_add_u32 v0, v29, 2, s0
	v_ashrrev_i32_e32 v29, 9, v27
	v_lshl_add_u32 v43, v29, 8, v0
	v_lshl_add_u64 v[40:41], v[30:31], 0, v[10:11]
	ds_read_b128 v[30:33], v43
	ds_read_b128 v[34:37], v34 offset:53248
	s_waitcnt lgkmcnt(2)
	global_store_dwordx4 v[40:41], v[18:21], off offset:2048
	ds_read_b128 v[18:21], v43 offset:16
	v_lshlrev_b32_e32 v40, 16, v22
	v_and_b32_e32 v41, 0xffff0000, v22
	s_waitcnt lgkmcnt(2)
	v_pk_mul_f32 v[30:31], v[30:31], v[40:41]
	v_readlane_b32 s16, v255, 24
	v_cvt_pk_bf16_f32 v22, v30, v31
	v_lshlrev_b32_e32 v30, 16, v23
	v_and_b32_e32 v31, 0xffff0000, v23
	v_pk_mul_f32 v[30:31], v[32:33], v[30:31]
	v_readlane_b32 s17, v255, 25
	v_cvt_pk_bf16_f32 v23, v30, v31
	v_lshlrev_b32_e32 v30, 16, v24
	v_and_b32_e32 v31, 0xffff0000, v24
	s_waitcnt lgkmcnt(0)
	v_pk_mul_f32 v[18:19], v[18:19], v[30:31]
	s_movk_i32 s3, 0x90
	v_cvt_pk_bf16_f32 v24, v18, v19
	v_lshlrev_b32_e32 v18, 16, v25
	v_and_b32_e32 v19, 0xffff0000, v25
	v_pk_mul_f32 v[18:19], v[20:21], v[18:19]
	v_lshl_add_u32 v20, v29, 6, s72
	v_cvt_pk_bf16_f32 v25, v18, v19
	v_bfe_u32 v18, v27, 3, 6
	v_add_u32_e32 v18, s86, v18
	v_mad_i64_i32 v[18:19], s[0:1], v18, s14, v[12:13]
	v_ashrrev_i32_e32 v21, 31, v20
	v_ashrrev_i32_e32 v29, 9, v39
	v_lshl_add_u64 v[18:19], v[20:21], 1, v[18:19]
	v_lshl_add_u32 v32, v29, 8, v0
	v_lshl_add_u64 v[30:31], v[18:19], 0, v[10:11]
	ds_read_b128 v[18:21], v32
	global_store_dwordx4 v[30:31], v[22:25], off offset:1024
	ds_read_b128 v[22:25], v32 offset:16
	v_lshlrev_b32_e32 v30, 16, v34
	v_and_b32_e32 v31, 0xffff0000, v34
	s_waitcnt lgkmcnt(1)
	v_pk_mul_f32 v[18:19], v[18:19], v[30:31]
	v_lshlrev_b32_e32 v30, 16, v35
	v_and_b32_e32 v31, 0xffff0000, v35
	v_pk_mul_f32 v[20:21], v[20:21], v[30:31]
	v_cvt_pk_bf16_f32 v18, v18, v19
	v_cvt_pk_bf16_f32 v19, v20, v21
	v_lshlrev_b32_e32 v20, 16, v36
	v_and_b32_e32 v21, 0xffff0000, v36
	s_waitcnt lgkmcnt(0)
	v_pk_mul_f32 v[20:21], v[22:23], v[20:21]
	v_lshlrev_b32_e32 v22, 16, v37
	v_and_b32_e32 v23, 0xffff0000, v37
	v_pk_mul_f32 v[22:23], v[24:25], v[22:23]
	v_cvt_pk_bf16_f32 v20, v20, v21
	v_cvt_pk_bf16_f32 v21, v22, v23
	v_and_b32_e32 v22, 63, v42
	v_add_u32_e32 v22, s86, v22
	v_lshl_add_u32 v24, v29, 6, s72
	v_mad_i64_i32 v[22:23], s[0:1], v22, s14, v[12:13]
	v_ashrrev_i32_e32 v25, 31, v24
	v_lshl_add_u64 v[22:23], v[24:25], 1, v[22:23]
	v_lshl_add_u64 v[34:35], v[22:23], 0, v[10:11]
	v_add_u32_e32 v22, 0x400, v27
	v_ashrrev_i32_e32 v29, 3, v22
	v_ashrrev_i32_e32 v36, 9, v22
	v_mad_u64_u32 v[22:23], s[0:1], v29, s2, v[38:39]
	ds_read_b128 v[22:25], v22 offset:53248
	v_lshl_add_u32 v37, v36, 8, v0
	ds_read_b128 v[30:33], v37
	global_store_dwordx4 v[34:35], v[18:21], off offset:1024
	ds_read_b128 v[18:21], v37 offset:16
	s_waitcnt lgkmcnt(2)
; __device__ __forceinline__ unsigned pack2(float a, float b) { f32v2_t v = {a, b}; bf16v2_t r = __builtin_convertvector(v, bf16v2_t); return __builtin_bit_cast(unsigned, r); }
; __device__ __forceinline__ bfr f2bf(float f) { return (bfr)(pack2(f, f) & 0xffffu); }
; __device__ __forceinline__ float fexp_(float x) { return __builtin_amdgcn_exp2f(x * 1.44269504f); }
; __device__ void ssd_pre(const KP& p, int l, int cid, int g) {
;     ...
; #pragma unroll
;   for (int it = 0; it < 4; ++it) {
;     int e = tid + 512 * it, xr = e >> 3, sg = e & 7, hh = xr >> 6, pp = xr & 63;
;     u32x4 v = *(const u32x4*)(xTs + xr * 72 + sg * 8), o;
; #pragma unroll
;     for (int k = 0; k < 4; ++k) {
;       float e0 = ev[hh * 64 + sg * 8 + 2 * k], e1 = ev[hh * 64 + sg * 8 + 2 * k + 1];
;       o[k] = pack2(__uint_as_float(v[k] << 16) * e0, __uint_as_float(v[k] & 0xffff0000u) * e1);
;     }
;     *(u32x4*)(proj + (size_t)(r0 + pp) * NIN + 512 + (g * 4 + hh) * 64 + sg * 8) = o;
;   }
;   for (int hh = 0; hh < 4; ++hh) {
;     const int h = g * 4 + hh;
;     const float Dh = p.in[16][l * 8 + h];
; #pragma unroll
;     for (int q = 0; q < 2; ++q) {
;       int t = w * 2 + q, ti = t >> 2, tj = t & 3, jx = tj * 16 + fr;
;       float cj = cumv[hh * 64 + jx], dj = dtv[hh * 64 + jx];
; #pragma unroll
;       for (int j = 0; j < 4; ++j) {
;         int i = ti * 16 + fq * 4 + j;
;         float gv = (tj <= ti && jx <= i) ? cb[q][j] * fexp_(cumv[hh * 64 + i] - cj) * dj : 0.f;
;         Gs[i * 72 + jx] = f2bf(gv);
	v_lshlrev_b32_e32 v34, 16, v22
	v_and_b32_e32 v35, 0xffff0000, v22
	s_waitcnt lgkmcnt(1)
	v_pk_mul_f32 v[30:31], v[30:31], v[34:35]
	v_lshlrev_b32_e32 v34, 16, v24
	v_and_b32_e32 v35, 0xffff0000, v24
	s_waitcnt lgkmcnt(0)
	v_pk_mul_f32 v[18:19], v[18:19], v[34:35]
	v_cvt_pk_bf16_f32 v22, v30, v31
	v_cvt_pk_bf16_f32 v24, v18, v19
	v_lshlrev_b32_e32 v18, 16, v25
	v_and_b32_e32 v19, 0xffff0000, v25
	v_pk_mul_f32 v[18:19], v[20:21], v[18:19]
	v_lshlrev_b32_e32 v30, 16, v23
	v_and_b32_e32 v31, 0xffff0000, v23
	v_add_u32_e32 v27, 0x600, v27
	v_cvt_pk_bf16_f32 v25, v18, v19
	v_and_b32_e32 v18, 63, v29
	v_pk_mul_f32 v[30:31], v[32:33], v[30:31]
	v_ashrrev_i32_e32 v37, 3, v27
	v_add_u32_e32 v18, s86, v18
	v_lshl_add_u32 v20, v36, 6, s72
	v_cvt_pk_bf16_f32 v23, v30, v31
	v_mad_u64_u32 v[30:31], s[0:1], v37, s2, v[38:39]
	v_mad_i64_i32 v[18:19], s[0:1], v18, s14, v[12:13]
	v_ashrrev_i32_e32 v21, 31, v20
	v_ashrrev_i32_e32 v27, 9, v27
	ds_read_b128 v[30:33], v30 offset:53248
	v_lshl_add_u64 v[18:19], v[20:21], 1, v[18:19]
	v_lshl_add_u32 v0, v27, 8, v0
	v_lshl_add_u64 v[34:35], v[18:19], 0, v[10:11]
	ds_read_b128 v[18:21], v0
	global_store_dwordx4 v[34:35], v[22:25], off offset:1024
	ds_read_b128 v[22:25], v0 offset:16
	s_waitcnt lgkmcnt(2)
	v_lshlrev_b32_e32 v34, 16, v30
	v_and_b32_e32 v35, 0xffff0000, v30
	v_lshlrev_b32_e32 v30, 16, v31
	v_and_b32_e32 v31, 0xffff0000, v31
	s_waitcnt lgkmcnt(1)
	v_pk_mul_f32 v[18:19], v[18:19], v[34:35]
	v_pk_mul_f32 v[20:21], v[20:21], v[30:31]
	v_cvt_pk_bf16_f32 v18, v18, v19
	v_cvt_pk_bf16_f32 v19, v20, v21
	v_lshlrev_b32_e32 v20, 16, v32
	v_and_b32_e32 v21, 0xffff0000, v32
	v_and_b32_e32 v0, 63, v37
	s_waitcnt lgkmcnt(0)
	v_pk_mul_f32 v[20:21], v[22:23], v[20:21]
	v_lshlrev_b32_e32 v22, 16, v33
	v_and_b32_e32 v23, 0xffff0000, v33
	v_add_u32_e32 v0, s86, v0
	v_pk_mul_f32 v[22:23], v[24:25], v[22:23]
	v_mad_i64_i32 v[12:13], s[0:1], v0, s14, v[12:13]
	s_lshl_b32 s2, s84, 2
	v_cvt_pk_bf16_f32 v20, v20, v21
	v_cvt_pk_bf16_f32 v21, v22, v23
	v_lshl_add_u32 v22, v27, 6, s72
	s_or_b32 s0, s2, s92
	v_ashrrev_i32_e32 v23, 31, v22
	s_ashr_i32 s1, s0, 31
	v_lshl_add_u64 v[12:13], v[22:23], 1, v[12:13]
	s_lshl_b64 s[0:1], s[0:1], 2
	v_lshl_add_u64 v[10:11], v[12:13], 0, v[10:11]
	s_add_u32 s0, s16, s0
	global_store_dwordx4 v[10:11], v[18:21], off offset:1024
	s_addc_u32 s1, s17, s1
	global_load_dword v33, v1, s[0:1]
	global_load_dword v120, v1, s[0:1] offset:4
	global_load_dword v121, v1, s[0:1] offset:8
	global_load_dword v122, v1, s[0:1] offset:12
	v_lshl_or_b32 v0, v14, 4, v15
	v_lshrrev_b32_e32 v12, 4, v26
	v_lshl_add_u32 v26, v0, 2, 0
	v_lshlrev_b32_e32 v11, 2, v12
	v_add_u32_e32 v10, 0x18800, v26
	v_lshl_or_b32 v13, v17, 4, v11
	v_add_u32_e32 v17, 0x18400, v26
	ds_read_b32 v25, v10
	ds_read_b32 v10, v17
	v_cmp_le_i32_e64 s[0:1], v0, v13
	s_xor_b64 s[76:77], s[38:39], -1
	s_and_b64 s[38:39], s[76:77], s[0:1]
	v_mov_b32_e32 v19, 0
	v_lshl_add_u32 v20, v13, 2, 0
	v_mov_b32_e32 v18, 0
	v_readlane_b32 s18, v255, 26
	v_readlane_b32 s19, v255, 27
	v_readlane_b32 s20, v255, 28
	v_readlane_b32 s21, v255, 29
	v_readlane_b32 s22, v255, 30
	v_readlane_b32 s23, v255, 31
	v_readlane_b32 s24, v255, 32
	v_readlane_b32 s25, v255, 33
	v_readlane_b32 s26, v255, 34
	v_readlane_b32 s27, v255, 35
	v_readlane_b32 s28, v255, 36
	v_readlane_b32 s29, v255, 37
	v_readlane_b32 s30, v255, 38
	v_readlane_b32 s31, v255, 39
	s_and_saveexec_b64 s[0:1], s[38:39]
	s_cbranch_execz .LBB0_715
	v_add_u32_e32 v17, 0x18800, v20
	ds_read_b32 v17, v17
	s_waitcnt lgkmcnt(0)
	v_sub_f32_e32 v17, v17, v25
	v_mul_f32_e32 v17, 0x3fb8aa3b, v17
	v_exp_f32_e32 v17, v17
	s_nop 0
	v_mul_f32_e32 v17, v6, v17
	v_mul_f32_e32 v17, v10, v17
	v_cvt_pk_bf16_f32 v18, v17, s0

; __device__ __forceinline__ bfr f2bf(float f) { return (bfr)(pack2(f, f) & 0xffffu); }
; __device__ __forceinline__ float bf2f(bfr b) { return __uint_as_float(((unsigned)b) << 16); }
; __device__ __forceinline__ float fexp_(float x) { return __builtin_amdgcn_exp2f(x * 1.44269504f); }
; __device__ void ssd_pre(const KP& p, int l, int cid, int g) {
;     ...
;   for (int hh = 0; hh < 4; ++hh) {
;     const int h = g * 4 + hh;
;     const float Dh = p.in[16][l * 8 + h];
; #pragma unroll
;     for (int q = 0; q < 2; ++q) {
;       int t = w * 2 + q, ti = t >> 2, tj = t & 3, jx = tj * 16 + fr;
;       float cj = cumv[hh * 64 + jx], dj = dtv[hh * 64 + jx];
; #pragma unroll
;       for (int j = 0; j < 4; ++j) {
;         int i = ti * 16 + fq * 4 + j;
;         float gv = (tj <= ti && jx <= i) ? cb[q][j] * fexp_(cumv[hh * 64 + i] - cj) * dj : 0.f;
;         Gs[i * 72 + jx] = f2bf(gv);
;       }
;     }
;     __syncthreads();
; #pragma unroll
;     for (int q = 0; q < 2; ++q) {
;       int t = w * 2 + q, ti = t >> 2, tp = t & 3;
;       f32x4 a = f32x4{0.f, 0.f, 0.f, 0.f};
;       a = mma_lds(Gs + ti * 16 * 72, 72, xTs + (hh * 64 + tp * 16) * 72, 72, 2, a, fr, fq);
;       int pp = tp * 16 + fr;
; #pragma unroll
;       for (int j = 0; j < 4; ++j) {
;         int i = ti * 16 + fq * 4 + j;
;         float y = a[j] + Dh * bf2f(xTs[(hh * 64 + pp) * 72 + i]);
;         mix[(size_t)(r0 + i) * DM + h * 64 + pp] = f2bf(y);
;       }
;     }
;     __syncthreads();
.LBB0_729:
	s_or_b64 exec, exec, s[84:85]
	s_waitcnt lgkmcnt(3)
	v_and_b32_e32 v16, -16, v28
	s_movk_i32 s14, 0x90
	v_lshlrev_b32_e32 v12, 3, v12
	v_mul_lo_u32 v17, v16, s14
	v_readlane_b32 s3, v254, 51
	v_mul_u32_u24_e32 v15, 0x48, v15
	v_lshlrev_b32_e32 v15, 1, v15
	v_add_u32_e32 v17, s3, v17
	v_lshlrev_b32_e32 v12, 1, v12
	v_add3_u32 v28, v17, v15, v12
	ds_write_b16 v25, v13 offset:432
	s_waitcnt lgkmcnt(0)
	s_barrier
	ds_read_b128 v[36:39], v28
	v_add_u32_e32 v15, 0, v15
	v_mul_u32_u24_e32 v13, 0x900, v14
	v_add3_u32 v30, v15, v12, v13
	ds_read_b128 v[12:15], v30 offset:53248
	ds_read_b128 v[40:43], v28 offset:64
	v_or_b32_e32 v11, v11, v16
	ds_read_b128 v[16:19], v30 offset:53312
	s_waitcnt lgkmcnt(2)
	v_mfma_f32_16x16x32_bf16 v[12:15], v[36:39], v[12:15], 0
	v_mad_u32_u24 v31, v0, s14, 0
	v_lshlrev_b32_e32 v29, 1, v11
	v_add_u32_e32 v34, v31, v29
	ds_read_b64 v[44:45], v34 offset:53248
	s_waitcnt lgkmcnt(1)
	v_mfma_f32_16x16x32_bf16 v[16:19], v[40:43], v[16:19], v[12:15]
	s_lshl_b32 s3, s72, 1
	s_add_u32 s84, s42, s3
	v_add_u32_e32 v48, s86, v11
	s_waitcnt lgkmcnt(0)
	v_lshlrev_b32_e32 v12, 16, v44
	s_addc_u32 s85, s43, 0
	s_waitcnt vmcnt(0)
	s_nop 0
	v_fma_f32 v12, v33, v12, v16
	v_ashrrev_i32_e32 v49, 31, v48
	v_lshl_add_u64 v[52:53], v[0:1], 1, s[84:85]
	v_cvt_pk_bf16_f32 v16, v12, s0
	v_lshlrev_b64 v[12:13], 11, v[48:49]
	v_lshl_add_u64 v[14:15], v[52:53], 0, v[12:13]
	global_store_short v[14:15], v16, off
	v_add_u32_e32 v14, 1, v48
	v_and_b32_e32 v11, 0xffff0000, v44
	v_ashrrev_i32_e32 v15, 31, v14
	v_fma_f32 v11, v33, v11, v17
	v_lshlrev_b64 v[14:15], 11, v[14:15]
	v_cvt_pk_bf16_f32 v11, v11, s0
	v_lshl_add_u64 v[16:17], v[52:53], 0, v[14:15]
	global_store_short v[16:17], v11, off
	v_add_u32_e32 v16, 2, v48
	v_lshlrev_b32_e32 v11, 16, v45
	v_ashrrev_i32_e32 v17, 31, v16
	v_fma_f32 v11, v33, v11, v18
	v_lshlrev_b64 v[16:17], 11, v[16:17]
	v_cvt_pk_bf16_f32 v11, v11, s0
	v_lshl_add_u64 v[46:47], v[52:53], 0, v[16:17]
	global_store_short v[46:47], v11, off
	v_and_b32_e32 v11, 0xffff0000, v45
	ds_read_b128 v[44:47], v30 offset:55552
	v_add_u32_e32 v18, 3, v48
	ds_read_b128 v[48:51], v30 offset:55616
	v_mad_u32_u24 v32, v10, s14, 0
	s_waitcnt lgkmcnt(1)
	v_mfma_f32_16x16x32_bf16 v[36:39], v[36:39], v[44:47], 0
	v_add_u32_e32 v35, v32, v29
	ds_read_b64 v[54:55], v35 offset:53248
	v_fmac_f32_e32 v19, v33, v11
	v_cvt_pk_bf16_f32 v11, v19, s0
	v_ashrrev_i32_e32 v19, 31, v18
	s_waitcnt lgkmcnt(1)
	v_mfma_f32_16x16x32_bf16 v[36:39], v[40:43], v[48:51], v[36:39]
	v_lshlrev_b64 v[18:19], 11, v[18:19]
	v_lshl_add_u64 v[44:45], v[52:53], 0, v[18:19]
	global_store_short v[44:45], v11, off
	v_mov_b32_e32 v11, v1
	s_waitcnt lgkmcnt(0)
	v_lshlrev_b32_e32 v42, 16, v54
	v_lshl_add_u64 v[40:41], v[10:11], 1, s[84:85]
	s_nop 0
	v_fma_f32 v36, v33, v42, v36
	v_cvt_pk_bf16_f32 v36, v36, s0
	v_lshl_add_u64 v[42:43], v[40:41], 0, v[12:13]
	global_store_short v[42:43], v36, off
	v_and_b32_e32 v36, 0xffff0000, v54
	v_fma_f32 v36, v33, v36, v37
	v_cvt_pk_bf16_f32 v42, v36, s0
	v_lshl_add_u64 v[36:37], v[40:41], 0, v[14:15]
	global_store_short v[36:37], v42, off
	v_lshlrev_b32_e32 v36, 16, v55
	v_fma_f32 v36, v33, v36, v38
	s_add_u32 s14, s2, s92
	v_cvt_pk_bf16_f32 v38, v36, s0
	v_lshl_add_u64 v[36:37], v[40:41], 0, v[16:17]
	s_addc_u32 s15, 0, s60
	global_store_short v[36:37], v38, off
	v_and_b32_e32 v36, 0xffff0000, v55
	s_lshl_b64 s[14:15], s[14:15], 2
	v_readlane_b32 s16, v255, 24
	v_fmac_f32_e32 v39, v33, v36
	v_readlane_b32 s17, v255, 25
	s_add_u32 s84, s16, s14
	v_cvt_pk_bf16_f32 v33, v39, s0
	v_lshl_add_u64 v[36:37], v[40:41], 0, v[18:19]
	s_addc_u32 s85, s17, s15
	global_store_short v[36:37], v33, off
	s_barrier
	v_mov_b32_e32 v33, v120
	v_add_u32_e32 v36, 0x18900, v26
	v_add_u32_e32 v38, 0x18500, v26
	ds_read_b32 v37, v36
	ds_read_b32 v36, v38
	v_mov_b32_e32 v38, 0
	v_mov_b32_e32 v39, 0
	v_readlane_b32 s18, v255, 26
	v_readlane_b32 s19, v255, 27
	v_readlane_b32 s20, v255, 28
	v_readlane_b32 s21, v255, 29
	v_readlane_b32 s22, v255, 30
	v_readlane_b32 s23, v255, 31
	v_readlane_b32 s24, v255, 32
	v_readlane_b32 s25, v255, 33
	v_readlane_b32 s26, v255, 34
	v_readlane_b32 s27, v255, 35
	v_readlane_b32 s28, v255, 36
	v_readlane_b32 s29, v255, 37
	v_readlane_b32 s30, v255, 38
	v_readlane_b32 s31, v255, 39
	s_and_saveexec_b64 s[86:87], s[38:39]
	s_cbranch_execz .LBB0_731
	v_add_u32_e32 v39, 0x18900, v20
	ds_read_b32 v39, v39
	s_waitcnt lgkmcnt(0)
	v_sub_f32_e32 v39, v39, v37
	v_mul_f32_e32 v39, 0x3fb8aa3b, v39
	v_exp_f32_e32 v39, v39
	s_nop 0
	v_mul_f32_e32 v39, v6, v39
	v_mul_f32_e32 v39, v36, v39
	v_cvt_pk_bf16_f32 v39, v39, s0

; __device__ __forceinline__ bfr f2bf(float f) { return (bfr)(pack2(f, f) & 0xffffu); }
; __device__ __forceinline__ float bf2f(bfr b) { return __uint_as_float(((unsigned)b) << 16); }
; __device__ __forceinline__ float fexp_(float x) { return __builtin_amdgcn_exp2f(x * 1.44269504f); }
; __device__ void ssd_pre(const KP& p, int l, int cid, int g) {
;     ...
;   for (int hh = 0; hh < 4; ++hh) {
;     const int h = g * 4 + hh;
;     const float Dh = p.in[16][l * 8 + h];
; #pragma unroll
;     for (int q = 0; q < 2; ++q) {
;       int t = w * 2 + q, ti = t >> 2, tj = t & 3, jx = tj * 16 + fr;
;       float cj = cumv[hh * 64 + jx], dj = dtv[hh * 64 + jx];
; #pragma unroll
;       for (int j = 0; j < 4; ++j) {
;         int i = ti * 16 + fq * 4 + j;
;         float gv = (tj <= ti && jx <= i) ? cb[q][j] * fexp_(cumv[hh * 64 + i] - cj) * dj : 0.f;
;         Gs[i * 72 + jx] = f2bf(gv);
;       }
;     }
;     __syncthreads();
; #pragma unroll
;     for (int q = 0; q < 2; ++q) {
;       int t = w * 2 + q, ti = t >> 2, tp = t & 3;
;       f32x4 a = f32x4{0.f, 0.f, 0.f, 0.f};
;       a = mma_lds(Gs + ti * 16 * 72, 72, xTs + (hh * 64 + tp * 16) * 72, 72, 2, a, fr, fq);
;       int pp = tp * 16 + fr;
; #pragma unroll
;       for (int j = 0; j < 4; ++j) {
;         int i = ti * 16 + fq * 4 + j;
;         float y = a[j] + Dh * bf2f(xTs[(hh * 64 + pp) * 72 + i]);
;         mix[(size_t)(r0 + i) * DM + h * 64 + pp] = f2bf(y);
;       }
;     }
;     __syncthreads();
.LBB0_745:
	s_or_b64 exec, exec, s[86:87]
	ds_write_b16 v25, v38 offset:432
	s_waitcnt lgkmcnt(0)
	s_barrier
	ds_read_b128 v[36:39], v28
	ds_read_b128 v[40:43], v30 offset:62464
	ds_read_b128 v[44:47], v28 offset:64
	ds_read_b128 v[48:51], v30 offset:62528
	ds_read_b64 v[52:53], v34 offset:62464
	s_waitcnt lgkmcnt(3)
	v_mfma_f32_16x16x32_bf16 v[40:43], v[36:39], v[40:43], 0
	s_lshl_b32 s2, s2, 7
	s_or_b32 s3, s2, 0x80
	s_add_u32 s14, s42, s3
	s_waitcnt lgkmcnt(1)
	v_mfma_f32_16x16x32_bf16 v[40:43], v[44:47], v[48:51], v[40:43]
	s_addc_u32 s15, s43, 0
	s_waitcnt lgkmcnt(0)
	v_lshlrev_b32_e32 v34, 16, v52
	v_lshl_add_u64 v[54:55], v[0:1], 1, s[14:15]
	v_lshl_add_u64 v[56:57], v[54:55], 0, v[12:13]
	v_add_u32_e32 v58, 0x900, v30
	s_nop 0
	s_nop 0
	v_fma_f32 v34, v33, v34, v40
	v_cvt_pk_bf16_f32 v34, v34, s0
	global_store_short v[56:57], v34, off
	v_and_b32_e32 v34, 0xffff0000, v52
	v_fma_f32 v34, v33, v34, v41
	v_cvt_pk_bf16_f32 v34, v34, s0
	v_lshl_add_u64 v[40:41], v[54:55], 0, v[14:15]
	global_store_short v[40:41], v34, off
	v_lshlrev_b32_e32 v34, 16, v53
	ds_read_b128 v[48:51], v58 offset:62464
	v_fma_f32 v34, v33, v34, v42
	v_cvt_pk_bf16_f32 v34, v34, s0
	v_lshl_add_u64 v[40:41], v[54:55], 0, v[16:17]
	global_store_short v[40:41], v34, off
	v_and_b32_e32 v34, 0xffff0000, v53
	v_fmac_f32_e32 v43, v33, v34
	v_cvt_pk_bf16_f32 v34, v43, s0
	ds_read_b128 v[40:43], v58 offset:62528
	s_waitcnt lgkmcnt(1)
	v_mfma_f32_16x16x32_bf16 v[36:39], v[36:39], v[48:51], 0
	ds_read_b64 v[50:51], v35 offset:62464
	v_lshl_add_u64 v[48:49], v[54:55], 0, v[18:19]
	global_store_short v[48:49], v34, off
	s_waitcnt lgkmcnt(1)
	v_mfma_f32_16x16x32_bf16 v[34:37], v[44:47], v[40:43], v[36:39]
	s_waitcnt lgkmcnt(0)
	v_lshlrev_b32_e32 v40, 16, v50
	s_nop 0
	v_lshl_add_u64 v[38:39], v[10:11], 1, s[14:15]
	s_nop 3
	v_fma_f32 v34, v33, v40, v34
	v_cvt_pk_bf16_f32 v34, v34, s0
	v_lshl_add_u64 v[40:41], v[38:39], 0, v[12:13]
	global_store_short v[40:41], v34, off
	v_and_b32_e32 v34, 0xffff0000, v50
	v_fma_f32 v34, v33, v34, v35
	v_cvt_pk_bf16_f32 v40, v34, s0
	v_lshl_add_u64 v[34:35], v[38:39], 0, v[14:15]
	global_store_short v[34:35], v40, off
	v_lshlrev_b32_e32 v34, 16, v51
	v_fma_f32 v34, v33, v34, v36
	v_cvt_pk_bf16_f32 v36, v34, s0
	v_lshl_add_u64 v[34:35], v[38:39], 0, v[16:17]
	global_store_short v[34:35], v36, off
	v_and_b32_e32 v34, 0xffff0000, v51
	v_fmac_f32_e32 v37, v33, v34
	v_cvt_pk_bf16_f32 v33, v37, s0
	v_lshl_add_u64 v[34:35], v[38:39], 0, v[18:19]
	global_store_short v[34:35], v33, off
	s_barrier
	v_mov_b32_e32 v34, v121
	v_add_u32_e32 v33, 0x18a00, v26
	v_add_u32_e32 v36, 0x18600, v26
	ds_read_b32 v35, v33
	ds_read_b32 v33, v36
	v_mov_b32_e32 v36, 0
	v_mov_b32_e32 v37, 0
	s_and_saveexec_b64 s[86:87], s[38:39]
	s_cbranch_execz .LBB0_747
	v_add_u32_e32 v37, 0x18a00, v20
	ds_read_b32 v37, v37
	s_waitcnt lgkmcnt(0)
	v_sub_f32_e32 v37, v37, v35
	v_mul_f32_e32 v37, 0x3fb8aa3b, v37
	v_exp_f32_e32 v37, v37
	s_nop 0
	v_mul_f32_e32 v37, v6, v37
	v_mul_f32_e32 v37, v33, v37
	v_cvt_pk_bf16_f32 v37, v37, s0

; __device__ __forceinline__ bfr f2bf(float f) { return (bfr)(pack2(f, f) & 0xffffu); }
; __device__ __forceinline__ float bf2f(bfr b) { return __uint_as_float(((unsigned)b) << 16); }
; __device__ __forceinline__ float fexp_(float x) { return __builtin_amdgcn_exp2f(x * 1.44269504f); }
; __device__ void ssd_pre(const KP& p, int l, int cid, int g) {
;     ...
;   for (int hh = 0; hh < 4; ++hh) {
;     const int h = g * 4 + hh;
;     const float Dh = p.in[16][l * 8 + h];
; #pragma unroll
;     for (int q = 0; q < 2; ++q) {
;       int t = w * 2 + q, ti = t >> 2, tj = t & 3, jx = tj * 16 + fr;
;       float cj = cumv[hh * 64 + jx], dj = dtv[hh * 64 + jx];
; #pragma unroll
;       for (int j = 0; j < 4; ++j) {
;         int i = ti * 16 + fq * 4 + j;
;         float gv = (tj <= ti && jx <= i) ? cb[q][j] * fexp_(cumv[hh * 64 + i] - cj) * dj : 0.f;
;         Gs[i * 72 + jx] = f2bf(gv);
;       }
;     }
;     __syncthreads();
; #pragma unroll
;     for (int q = 0; q < 2; ++q) {
;       int t = w * 2 + q, ti = t >> 2, tp = t & 3;
;       f32x4 a = f32x4{0.f, 0.f, 0.f, 0.f};
;       a = mma_lds(Gs + ti * 16 * 72, 72, xTs + (hh * 64 + tp * 16) * 72, 72, 2, a, fr, fq);
;       int pp = tp * 16 + fr;
; #pragma unroll
;       for (int j = 0; j < 4; ++j) {
;         int i = ti * 16 + fq * 4 + j;
;         float y = a[j] + Dh * bf2f(xTs[(hh * 64 + pp) * 72 + i]);
;         mix[(size_t)(r0 + i) * DM + h * 64 + pp] = f2bf(y);
;       }
;     }
;     __syncthreads();
.LBB0_761:
	s_or_b64 exec, exec, s[86:87]
	ds_write_b16 v25, v36 offset:432
	s_waitcnt lgkmcnt(0)
	s_barrier
	ds_read_b128 v[36:39], v28
	v_add_u32_e32 v33, 0xd000, v30
	ds_read_b128 v[40:43], v33 offset:18432
	ds_read_b128 v[44:47], v28 offset:64
	s_or_b32 s3, s2, 0x100
	ds_read_b128 v[48:51], v33 offset:18496
	s_add_u32 s14, s42, s3
	s_waitcnt lgkmcnt(2)
	v_mfma_f32_16x16x32_bf16 v[40:43], v[36:39], v[40:43], 0
	s_mov_b32 s3, 0xd000
	v_add3_u32 v31, v31, v29, s3
	ds_read_b64 v[52:53], v31 offset:18432
	s_waitcnt lgkmcnt(1)
	v_mfma_f32_16x16x32_bf16 v[40:43], v[44:47], v[48:51], v[40:43]
	s_addc_u32 s15, s43, 0
	v_add3_u32 v29, v32, v29, s3
	v_lshl_add_u64 v[56:57], v[0:1], 1, s[14:15]
	s_waitcnt lgkmcnt(0)
	v_lshlrev_b32_e32 v32, 16, v52
	v_lshl_add_u64 v[48:49], v[56:57], 0, v[12:13]
	s_nop 0
	s_nop 0
	v_fma_f32 v32, v34, v32, v40
	v_cvt_pk_bf16_f32 v32, v32, s0
	global_store_short v[48:49], v32, off
	v_and_b32_e32 v32, 0xffff0000, v52
	v_add_u32_e32 v30, 0xd900, v30
	v_fma_f32 v32, v34, v32, v41
	ds_read_b64 v[58:59], v29 offset:18432
	ds_read_b128 v[48:51], v30 offset:18432
	v_cvt_pk_bf16_f32 v32, v32, s0
	v_lshl_add_u64 v[40:41], v[56:57], 0, v[14:15]
	global_store_short v[40:41], v32, off
	v_lshlrev_b32_e32 v32, 16, v53
	v_fma_f32 v32, v34, v32, v42
	v_cvt_pk_bf16_f32 v32, v32, s0
	v_lshl_add_u64 v[40:41], v[56:57], 0, v[16:17]
	global_store_short v[40:41], v32, off
	v_and_b32_e32 v32, 0xffff0000, v53
	ds_read_b128 v[52:55], v30 offset:18496
	s_waitcnt lgkmcnt(1)
	v_mfma_f32_16x16x32_bf16 v[36:39], v[36:39], v[48:51], 0
	v_fmac_f32_e32 v43, v34, v32
	v_cvt_pk_bf16_f32 v32, v43, s0
	v_lshl_add_u64 v[40:41], v[56:57], 0, v[18:19]
	s_waitcnt lgkmcnt(0)
	v_mfma_f32_16x16x32_bf16 v[36:39], v[44:47], v[52:55], v[36:39]
	global_store_short v[40:41], v32, off
	v_lshlrev_b32_e32 v32, 16, v58
	v_lshl_add_u64 v[40:41], v[10:11], 1, s[14:15]
	v_lshl_add_u64 v[42:43], v[40:41], 0, v[12:13]
	s_nop 3
	v_fma_f32 v32, v34, v32, v36
	v_cvt_pk_bf16_f32 v32, v32, s0
	global_store_short v[42:43], v32, off
	v_and_b32_e32 v32, 0xffff0000, v58
	v_fma_f32 v32, v34, v32, v37
	v_cvt_pk_bf16_f32 v32, v32, s0
	v_lshl_add_u64 v[36:37], v[40:41], 0, v[14:15]
	global_store_short v[36:37], v32, off
	v_lshlrev_b32_e32 v32, 16, v59
	v_fma_f32 v32, v34, v32, v38
	v_cvt_pk_bf16_f32 v32, v32, s0
	v_lshl_add_u64 v[36:37], v[40:41], 0, v[16:17]
	global_store_short v[36:37], v32, off
	v_and_b32_e32 v32, 0xffff0000, v59
	v_fmac_f32_e32 v39, v34, v32
	v_cvt_pk_bf16_f32 v32, v39, s0
	v_lshl_add_u64 v[34:35], v[40:41], 0, v[18:19]
	global_store_short v[34:35], v32, off
	s_barrier
	v_mov_b32_e32 v32, v122
	v_add_u32_e32 v34, 0x18b00, v26
	v_add_u32_e32 v26, 0x18700, v26
	ds_read_b32 v34, v34
	ds_read_b32 v26, v26
	v_mov_b32_e32 v35, 0
	v_mov_b32_e32 v36, 0
	s_and_saveexec_b64 s[84:85], s[38:39]
	s_cbranch_execz .LBB0_763
	v_add_u32_e32 v36, 0x18b00, v20
	ds_read_b32 v36, v36
	s_waitcnt lgkmcnt(0)
	v_sub_f32_e32 v36, v36, v34
	v_mul_f32_e32 v36, 0x3fb8aa3b, v36
	v_exp_f32_e32 v36, v36
	s_nop 0
	v_mul_f32_e32 v6, v6, v36
	v_mul_f32_e32 v6, v26, v6
	v_cvt_pk_bf16_f32 v36, v6, s0
